# attention: static s_setprio 1 for waves 0-3 instead (other half), for comparison
# speedup vs baseline: 1.0055x; 1.0022x over previous
.LBB0_383:
	s_add_u32 s4, s58, 0x100000
	s_addc_u32 s5, s59, 0
	v_writelane_b32 v255, s4, 22
	v_and_b32_e32 v0, 63, v6
	s_nop 0
	v_writelane_b32 v255, s5, 23
	s_nop 0
	v_readlane_b32 s4, v255, 16
	v_readlane_b32 s5, v255, 17
	s_and_b64 vcc, exec, s[4:5]
	s_cbranch_vccnz .LBB0_429
	v_mov_b32_e32 v88, 0
	v_and_b32_e32 v2, 0x70, v8
	v_mov_b32_e32 v3, v88
	v_add_u32_e32 v1, 0, v2
	v_lshl_add_u64 v[136:137], s[42:43], 0, v[2:3]
	v_add_u32_e32 v2, 0x200, v6
	v_ashrrev_i32_e32 v177, 3, v2
	v_add_u32_e32 v2, 0x400, v6
	v_ashrrev_i32_e32 v179, 3, v2
	v_add_u32_e32 v2, 0x600, v6
	s_ashr_i32 s4, s35, 7
	v_ashrrev_i32_e32 v181, 3, v2
	v_add_u32_e32 v2, 0x800, v6
	v_writelane_b32 v255, s4, 24
	v_ashrrev_i32_e32 v183, 3, v2
	v_add_u32_e32 v2, 0xa00, v6
	v_cmp_gt_u32_e64 s[4:5], 32, v0
	v_and_b32_e32 v0, 3, v6
	v_ashrrev_i32_e32 v185, 3, v2
	v_lshlrev_b32_e32 v4, 1, v6
	v_lshrrev_b32_e32 v2, 1, v6
	s_movk_i32 s83, 0x90
	v_lshlrev_b32_e32 v0, 3, v0
	s_lshl_b32 s81, s34, 5
	v_lshlrev_b32_e32 v134, 3, v7
	v_and_b32_e32 v3, 19, v6
	v_and_b32_e32 v5, 8, v4
	v_and_b32_e32 v8, 4, v2
	v_lshrrev_b32_e32 v9, 2, v6
	v_lshlrev_b32_e32 v2, 2, v7
	v_mul_lo_u32 v7, v176, s83
	v_mul_lo_u32 v10, v177, s83
	v_mul_lo_u32 v11, v179, s83
	v_mul_lo_u32 v12, v181, s83
	v_mul_lo_u32 v13, v183, s83
	v_mul_lo_u32 v14, v185, s83
	v_and_or_b32 v138, v4, 32, v0
	s_mov_b32 s34, 0x41a00000
	s_mov_b32 s36, 2.0
	s_mov_b32 s60, 4.0
	s_mov_b32 s62, 0x40c00000
	s_mov_b32 s64, 0x41800000
	s_mov_b32 s70, 0x41900000
	s_mov_b32 s72, 0x41b00000
	v_mbcnt_lo_u32_b32 v0, -1, 0
	s_mov_b32 s15, 0
	s_and_b32 s82, s81, 32
	v_add_u32_e32 v133, 0xffffff80, v176
	v_add_u32_e32 v178, 0xffffff80, v177
	v_add_u32_e32 v180, 0xffffff80, v179
	v_add_u32_e32 v182, 0xffffff80, v181
	v_add_u32_e32 v184, 0xffffff80, v183
	v_add_u32_e32 v186, 0xffffff80, v185
	v_cndmask_b32_e64 v187, 0, 1.0, s[4:5]
	v_sub_u32_e32 v188, v139, v134
	v_and_or_b32 v189, v9, 3, v134
	v_or3_b32 v190, v3, v5, v8
	v_add_u32_e32 v191, v1, v7
	v_add_u32_e32 v192, v1, v10
	v_add_u32_e32 v193, v1, v11
	v_add_u32_e32 v194, v1, v12
	v_add_u32_e32 v195, v1, v13
	v_add_u32_e32 v196, v1, v14
	s_movk_i32 s84, 0x1800
	s_mov_b32 s35, 0x41a80000
	s_mov_b32 s37, 0x40400000
	s_mov_b32 s61, 0x40a00000
	s_mov_b32 s63, 0x40e00000
	s_mov_b32 s65, 0x41880000
	s_mov_b32 s71, 0x41980000
	s_mov_b32 s73, 0x41b80000
	s_mov_b32 s85, 0xff800000
	v_lshlrev_b32_e32 v140, 1, v2
	v_mov_b32_e32 v197, 0x3fb8aa3b
	v_mov_b32_e32 v198, 0x42800000
	v_mbcnt_hi_u32_b32 v199, -1, v0
	v_mov_b32_e32 v200, 0xff800000
	s_mov_b32 s86, s2
	s_waitcnt vmcnt(0)
	v_readfirstlane_b32 s98, v254
	s_nop 3
	s_lshr_b32 s98, s98, 6
	s_cmp_lt_u32 s98, 4
	s_cbranch_scc0 .Lsp3
	s_setprio 1

.LBB0_1243:
	v_readlane_b32 s8, v255, 16
	v_readlane_b32 s9, v255, 17
	v_and_b32_e32 v0, 63, v6
	s_and_b64 vcc, exec, s[8:9]
	s_cbranch_vccnz .LBB0_1289
	v_mov_b32_e32 v88, 0
	v_and_b32_e32 v2, 0x70, v8
	v_mov_b32_e32 v3, v88
	v_add_u32_e32 v1, 0, v2
	v_lshl_add_u64 v[136:137], s[42:43], 0, v[2:3]
	v_add_u32_e32 v2, 0x200, v6
	v_ashrrev_i32_e32 v177, 3, v2
	v_add_u32_e32 v2, 0x400, v6
	v_ashrrev_i32_e32 v179, 3, v2
	v_add_u32_e32 v2, 0x600, v6
	v_ashrrev_i32_e32 v181, 3, v2
	v_add_u32_e32 v2, 0x800, v6
	s_ashr_i32 s5, s35, 7
	v_ashrrev_i32_e32 v183, 3, v2
	v_add_u32_e32 v2, 0xa00, v6
	v_cmp_gt_u32_e64 s[8:9], 32, v0
	v_and_b32_e32 v0, 3, v6
	v_writelane_b32 v255, s5, 50
	s_lshl_b32 s5, s34, 5
	v_ashrrev_i32_e32 v185, 3, v2
	v_lshlrev_b32_e32 v4, 1, v6
	v_lshrrev_b32_e32 v2, 1, v6
	s_movk_i32 s71, 0x90
	v_lshlrev_b32_e32 v0, 3, v0
	v_writelane_b32 v255, s5, 52
	s_and_b32 s5, s5, 32
	v_lshlrev_b32_e32 v134, 3, v7
	v_and_b32_e32 v3, 19, v6
	v_and_b32_e32 v5, 8, v4
	v_and_b32_e32 v8, 4, v2
	v_lshrrev_b32_e32 v9, 2, v6
	v_lshlrev_b32_e32 v2, 2, v7
	v_mul_lo_u32 v7, v176, s71
	v_mul_lo_u32 v10, v177, s71
	v_mul_lo_u32 v11, v179, s71
	v_mul_lo_u32 v12, v181, s71
	v_mul_lo_u32 v13, v183, s71
	v_mul_lo_u32 v14, v185, s71
	v_and_or_b32 v138, v4, 32, v0
	s_mov_b32 s34, 0x41a00000
	s_mov_b32 s36, 2.0
	s_mov_b32 s60, 4.0
	s_mov_b32 s82, 0x40c00000
	s_mov_b32 s88, 0x41800000
	s_mov_b32 s92, 0x41900000
	s_mov_b32 s94, 0x41b00000
	v_mbcnt_lo_u32_b32 v0, -1, 0
	s_mov_b32 s15, 0
	v_writelane_b32 v255, s5, 53
	v_add_u32_e32 v133, 0xffffff80, v176
	v_add_u32_e32 v178, 0xffffff80, v177
	v_add_u32_e32 v180, 0xffffff80, v179
	v_add_u32_e32 v182, 0xffffff80, v181
	v_add_u32_e32 v184, 0xffffff80, v183
	v_add_u32_e32 v186, 0xffffff80, v185
	v_cndmask_b32_e64 v187, 0, 1.0, s[8:9]
	v_sub_u32_e32 v188, v139, v134
	v_and_or_b32 v189, v9, 3, v134
	v_or3_b32 v190, v3, v5, v8
	v_add_u32_e32 v191, v1, v7
	v_add_u32_e32 v192, v1, v10
	v_add_u32_e32 v193, v1, v11
	v_add_u32_e32 v194, v1, v12
	v_add_u32_e32 v195, v1, v13
	v_add_u32_e32 v196, v1, v14
	s_movk_i32 s72, 0x1800
	s_mov_b32 s35, 0x41a80000
	s_mov_b32 s37, 0x40400000
	s_mov_b32 s61, 0x40a00000
	s_mov_b32 s83, 0x40e00000
	s_mov_b32 s89, 0x41880000
	s_mov_b32 s93, 0x41980000
	s_mov_b32 s95, 0x41b80000
	s_mov_b32 s73, 0xff800000
	v_lshlrev_b32_e32 v140, 1, v2
	v_mov_b32_e32 v197, 0x3fb8aa3b
	v_mov_b32_e32 v198, 0x42800000
	v_mbcnt_hi_u32_b32 v199, -1, v0
	v_mov_b32_e32 v200, 0xff800000
	s_mov_b32 s78, s2
	s_waitcnt vmcnt(0)
	v_readfirstlane_b32 s98, v254
	s_nop 3
	s_lshr_b32 s98, s98, 6
	s_cmp_lt_u32 s98, 4
	s_cbranch_scc0 .Lsp11
	s_setprio 1

.LBB0_2103:
	v_readlane_b32 s8, v255, 16
	v_readlane_b32 s9, v255, 17
	v_and_b32_e32 v0, 63, v6
	s_and_b64 vcc, exec, s[8:9]
	s_cbranch_vccnz .LBB0_2150
	v_mov_b32_e32 v88, 0
	v_and_b32_e32 v2, 0x70, v8
	v_mov_b32_e32 v3, v88
	v_add_u32_e32 v1, 0, v2
	v_lshl_add_u64 v[136:137], s[42:43], 0, v[2:3]
	v_add_u32_e32 v2, 0x200, v6
	v_ashrrev_i32_e32 v177, 3, v2
	v_add_u32_e32 v2, 0x400, v6
	v_ashrrev_i32_e32 v179, 3, v2
	v_add_u32_e32 v2, 0x600, v6
	v_ashrrev_i32_e32 v181, 3, v2
	v_add_u32_e32 v2, 0x800, v6
	v_ashrrev_i32_e32 v183, 3, v2
	v_add_u32_e32 v2, 0xa00, v6
	v_cmp_gt_u32_e64 s[10:11], 32, v0
	v_and_b32_e32 v0, 3, v6
	s_ashr_i32 s5, s35, 7
	s_lshl_b32 s69, s34, 5
	v_ashrrev_i32_e32 v185, 3, v2
	v_lshlrev_b32_e32 v4, 1, v6
	v_lshrrev_b32_e32 v2, 1, v6
	s_movk_i32 s71, 0x90
	v_lshlrev_b32_e32 v0, 3, v0
	v_writelane_b32 v255, s5, 52
	s_and_b32 s5, s69, 32
	v_lshlrev_b32_e32 v134, 3, v7
	v_and_b32_e32 v3, 19, v6
	v_and_b32_e32 v5, 8, v4
	v_and_b32_e32 v8, 4, v2
	v_lshrrev_b32_e32 v9, 2, v6
	v_lshlrev_b32_e32 v2, 2, v7
	v_mul_lo_u32 v7, v176, s71
	v_mul_lo_u32 v10, v177, s71
	v_mul_lo_u32 v11, v179, s71
	v_mul_lo_u32 v12, v181, s71
	v_mul_lo_u32 v13, v183, s71
	v_mul_lo_u32 v14, v185, s71
	v_and_or_b32 v138, v4, 32, v0
	s_mov_b32 s34, 0x41a00000
	s_mov_b32 s36, 2.0
	s_mov_b32 s60, 4.0
	s_mov_b32 s82, 0x40c00000
	s_mov_b32 s88, 0x41800000
	s_mov_b32 s94, 0x41900000
	s_mov_b32 s96, 0x41b00000
	v_mbcnt_lo_u32_b32 v0, -1, 0
	s_mov_b32 s9, 0
	v_writelane_b32 v255, s5, 53
	v_add_u32_e32 v133, 0xffffff80, v176
	v_add_u32_e32 v178, 0xffffff80, v177
	v_add_u32_e32 v180, 0xffffff80, v179
	v_add_u32_e32 v182, 0xffffff80, v181
	v_add_u32_e32 v184, 0xffffff80, v183
	v_add_u32_e32 v186, 0xffffff80, v185
	v_cndmask_b32_e64 v187, 0, 1.0, s[10:11]
	v_sub_u32_e32 v188, v139, v134
	v_and_or_b32 v189, v9, 3, v134
	v_or3_b32 v190, v3, v5, v8
	v_add_u32_e32 v191, v1, v7
	v_add_u32_e32 v192, v1, v10
	v_add_u32_e32 v193, v1, v11
	v_add_u32_e32 v194, v1, v12
	v_add_u32_e32 v195, v1, v13
	v_add_u32_e32 v196, v1, v14
	s_movk_i32 s72, 0x1800
	s_mov_b32 s35, 0x41a80000
	s_mov_b32 s37, 0x40400000
	s_mov_b32 s61, 0x40a00000
	s_mov_b32 s83, 0x40e00000
	s_mov_b32 s89, 0x41880000
	s_mov_b32 s95, 0x41980000
	s_mov_b32 s97, 0x41b80000
	s_mov_b32 s73, 0xff800000
	v_lshlrev_b32_e32 v140, 1, v2
	v_mov_b32_e32 v197, 0x3fb8aa3b
	v_mov_b32_e32 v198, 0x42800000
	v_mbcnt_hi_u32_b32 v199, -1, v0
	v_mov_b32_e32 v200, 0xff800000
	s_mov_b32 s78, s2
	s_waitcnt vmcnt(0)
	v_readfirstlane_b32 s98, v254
	s_nop 3
	s_lshr_b32 s98, s98, 6
	s_cmp_lt_u32 s98, 4
	s_cbranch_scc0 .Lsp19
	s_setprio 1

.LBB0_2967:
	v_readlane_b32 s6, v255, 16
	v_readlane_b32 s7, v255, 17
	v_and_b32_e32 v0, 63, v6
	s_and_b64 vcc, exec, s[6:7]
	s_cbranch_vccnz .LBB0_3013
	v_mov_b32_e32 v88, 0
	v_and_b32_e32 v2, 0x70, v8
	v_mov_b32_e32 v3, v88
	v_add_u32_e32 v1, 0, v2
	v_lshl_add_u64 v[136:137], s[42:43], 0, v[2:3]
	v_add_u32_e32 v2, 0x200, v6
	v_ashrrev_i32_e32 v177, 3, v2
	v_add_u32_e32 v2, 0x400, v6
	v_ashrrev_i32_e32 v179, 3, v2
	v_add_u32_e32 v2, 0x600, v6
	v_ashrrev_i32_e32 v181, 3, v2
	v_add_u32_e32 v2, 0x800, v6
	v_ashrrev_i32_e32 v183, 3, v2
	v_add_u32_e32 v2, 0xa00, v6
	v_cmp_gt_u32_e64 s[6:7], 32, v0
	v_and_b32_e32 v0, 3, v6
	v_ashrrev_i32_e32 v185, 3, v2
	v_lshlrev_b32_e32 v4, 1, v6
	v_lshrrev_b32_e32 v2, 1, v6
	s_movk_i32 s65, 0x90
	v_lshlrev_b32_e32 v0, 3, v0
	s_ashr_i32 s60, s19, 7
	s_lshl_b32 s61, s18, 5
	v_lshlrev_b32_e32 v134, 3, v7
	v_and_b32_e32 v3, 19, v6
	v_and_b32_e32 v5, 8, v4
	v_and_b32_e32 v8, 4, v2
	v_lshrrev_b32_e32 v9, 2, v6
	v_lshlrev_b32_e32 v2, 2, v7
	v_mul_lo_u32 v7, v176, s65
	v_mul_lo_u32 v10, v177, s65
	v_mul_lo_u32 v11, v179, s65
	v_mul_lo_u32 v12, v181, s65
	v_mul_lo_u32 v13, v183, s65
	v_mul_lo_u32 v14, v185, s65
	v_and_or_b32 v138, v4, 32, v0
	s_mov_b32 s18, 0x41a00000
	s_mov_b32 s22, 2.0
	s_mov_b32 s24, 4.0
	s_mov_b32 s26, 0x40c00000
	s_mov_b32 s34, 0x41800000
	s_mov_b32 s36, 0x41900000
	s_mov_b32 s48, 0x41b00000
	v_mbcnt_lo_u32_b32 v0, -1, 0
	s_mov_b32 s17, 0
	s_and_b32 s64, s61, 32
	v_add_u32_e32 v133, 0xffffff80, v176
	v_add_u32_e32 v178, 0xffffff80, v177
	v_add_u32_e32 v180, 0xffffff80, v179
	v_add_u32_e32 v182, 0xffffff80, v181
	v_add_u32_e32 v184, 0xffffff80, v183
	v_add_u32_e32 v186, 0xffffff80, v185
	v_cndmask_b32_e64 v187, 0, 1.0, s[6:7]
	v_sub_u32_e32 v188, v139, v134
	v_and_or_b32 v189, v9, 3, v134
	v_or3_b32 v190, v3, v5, v8
	v_add_u32_e32 v191, v1, v7
	v_add_u32_e32 v192, v1, v10
	v_add_u32_e32 v193, v1, v11
	v_add_u32_e32 v194, v1, v12
	v_add_u32_e32 v195, v1, v13
	v_add_u32_e32 v196, v1, v14
	s_movk_i32 s66, 0x1800
	s_mov_b32 s19, 0x41a80000
	s_mov_b32 s23, 0x40400000
	s_mov_b32 s25, 0x40a00000
	s_mov_b32 s27, 0x40e00000
	s_mov_b32 s35, 0x41880000
	s_mov_b32 s37, 0x41980000
	s_mov_b32 s49, 0x41b80000
	s_mov_b32 s67, 0xff800000
	v_lshlrev_b32_e32 v140, 1, v2
	v_mov_b32_e32 v197, 0x3fb8aa3b
	v_mov_b32_e32 v198, 0x42800000
	v_mbcnt_hi_u32_b32 v199, -1, v0
	v_mov_b32_e32 v200, 0xff800000
	s_mov_b32 s68, s2
	s_waitcnt vmcnt(0)
	v_readfirstlane_b32 s98, v254
	s_nop 3
	s_lshr_b32 s98, s98, 6
	s_cmp_lt_u32 s98, 4
	s_cbranch_scc0 .Lsp27
	s_setprio 1
